# unitC: mhat==0 fast path with bfe+bfi bitmap masking on table values read into accumulators; no K/V prefetch drain in QK
# speedup vs baseline: 1.0268x; 1.0123x over previous
; __device__ __forceinline__ int crowc(int r) { return (r & 3) + 8 * (r >> 2); }
; template <int D, int DV, bool TAB, bool BITS, int KT> ...
;     ...
;                 if (TAB) {
; #pragma unroll
;                     for (int r = 0; r < 16; ++r) p0[r] = tabL[tj + crowc(r)];
; #pragma unroll
;                     for (int r = 0; r < 16; ++r) p1[r] = tabL[tj + 32 + crowc(r)];
;                     __builtin_amdgcn_sched_barrier(0);
; #pragma unroll
;                     for (int r = 0; r < 16; ++r) { p0[r] -= mhat; p1[r] -= mhat; }
;                 } else {
; #pragma unroll
;                     for (int r = 0; r < 16; ++r) { p0[r] = nm; p1[r] = nm; }
;                 }
;                 if (BITS) {
; #pragma unroll
;                     for (int r = 0; r < 16; ++r) { const int off = crowc(r); if (!((w0 >> off) & 1u)) p0[r] = NEGV; if (!((w1 >> off) & 1u)) p1[r] = NEGV; } }
; #pragma unroll
;                 for (int k4 = 0; k4 < D / 16; k4 += KG) {
;                     bf16x8 ka[KG], kb[KG];
; #pragma unroll
;                     for (int kk = 0; kk < KG; ++kk) { ka[kk] = *(const bf16x8*)(Kl + r32 * KP + ((k4 + kk) * 16 + 8 * hi) * 2); kb[kk] = *(const bf16x8*)(Kl + (32 + r32) * KP + ((k4 + kk) * 16 + 8 * hi) * 2); }
;                     __builtin_amdgcn_sched_barrier(0);
; #pragma unroll
;                     for (int kk = 0; kk < KG; ++kk) { p0 = __builtin_amdgcn_mfma_f32_32x32x16_bf16(ka[kk], qf[k4 + kk], p0, 0, 0, 0); p1 = __builtin_amdgcn_mfma_f32_32x32x16_bf16(kb[kk], qf[k4 + kk], p1, 0, 0, 0); }
;                     __builtin_amdgcn_sched_barrier(0);
;                 }
.Lslow_qk_c0:
	ds_read2_b32 v[34:35], v138 offset0:1 offset1:2
	ds_read2_b32 v[36:37], v138 offset1:3
	ds_read2_b32 v[38:39], v138 offset0:8 offset1:9
	ds_read2_b32 v[40:41], v138 offset0:10 offset1:11
	ds_read2_b32 v[42:43], v138 offset0:16 offset1:17
	ds_read2_b32 v[44:45], v138 offset0:18 offset1:19
	ds_read2_b32 v[46:47], v138 offset0:24 offset1:25
	ds_read2_b32 v[48:49], v138 offset0:26 offset1:27
	ds_read_b128 v[142:145], v141
	ds_read_b128 v[146:149], v141 offset:32
	ds_read_b128 v[150:153], v141 offset:64
	ds_read_b128 v[154:157], v141 offset:96
	ds_read2_b32 v[174:175], v138 offset0:32 offset1:35
	ds_read2_b32 v[176:177], v138 offset0:33 offset1:34
	ds_read2_b32 v[178:179], v138 offset0:40 offset1:41
	ds_read2_b32 v[180:181], v138 offset0:42 offset1:43
	ds_read2_b32 v[182:183], v138 offset0:48 offset1:49
	ds_read2_b32 v[184:185], v138 offset0:50 offset1:51
	ds_read2_b32 v[188:189], v138 offset0:56 offset1:57
	ds_read2_b32 v[190:191], v138 offset0:58 offset1:59
	ds_read_b128 v[158:161], v141 offset:4608
	ds_read_b128 v[162:165], v141 offset:4640
	ds_read_b128 v[166:169], v141 offset:4672
	ds_read_b128 v[170:173], v141 offset:4704
	v_lshrrev_b32_e32 v65, v134, v102
	v_and_b32_e32 v50, 1, v65
	s_waitcnt lgkmcnt(14)
	v_sub_f32_e32 v36, v36, v139
	v_cmp_eq_u32_e32 vcc, 1, v50
	v_sub_f32_e32 v34, v34, v139
	s_nop 0
	v_cndmask_b32_e32 v50, v237, v36, vcc
	v_and_b32_e32 v36, 2, v65
	v_cmp_ne_u32_e32 vcc, 0, v36
	s_nop 1
	v_cndmask_b32_e32 v51, v237, v34, vcc
	v_sub_f32_e32 v34, v35, v139
	v_and_b32_e32 v35, 4, v65
	v_cmp_ne_u32_e32 vcc, 0, v35
	v_and_b32_e32 v35, 8, v65
	s_nop 0
	v_cndmask_b32_e32 v52, v237, v34, vcc
	v_sub_f32_e32 v34, v37, v139
	v_cmp_ne_u32_e32 vcc, 0, v35
	v_and_b32_e32 v35, 0x100, v65
	s_nop 0
	v_cndmask_b32_e32 v53, v237, v34, vcc
	v_sub_f32_e32 v34, v38, v139
	v_cmp_ne_u32_e32 vcc, 0, v35
	v_and_b32_e32 v35, 0x200, v65
	s_nop 0
	v_cndmask_b32_e32 v54, v237, v34, vcc
	v_sub_f32_e32 v34, v39, v139
	v_cmp_ne_u32_e32 vcc, 0, v35
	v_and_b32_e32 v35, 0x400, v65
	s_nop 0
	v_cndmask_b32_e32 v55, v237, v34, vcc
	v_sub_f32_e32 v34, v40, v139
	v_cmp_ne_u32_e32 vcc, 0, v35
	v_and_b32_e32 v35, 0x800, v65
	s_nop 0
	v_cndmask_b32_e32 v56, v237, v34, vcc
	v_sub_f32_e32 v34, v41, v139
	v_cmp_ne_u32_e32 vcc, 0, v35
	v_and_b32_e32 v35, 0x10000, v65
	s_nop 0
	v_cndmask_b32_e32 v57, v237, v34, vcc
	v_sub_f32_e32 v34, v42, v139
	v_cmp_ne_u32_e32 vcc, 0, v35
	v_and_b32_e32 v35, 0x20000, v65
	s_nop 0
	v_cndmask_b32_e32 v58, v237, v34, vcc
	v_sub_f32_e32 v34, v43, v139
	v_cmp_ne_u32_e32 vcc, 0, v35
	v_and_b32_e32 v35, 0x40000, v65
	s_nop 0
	v_cndmask_b32_e32 v59, v237, v34, vcc
	v_sub_f32_e32 v34, v44, v139
	v_cmp_ne_u32_e32 vcc, 0, v35
	v_and_b32_e32 v35, 0x80000, v65
	s_nop 0
	v_cndmask_b32_e32 v60, v237, v34, vcc
	v_sub_f32_e32 v34, v45, v139
	v_cmp_ne_u32_e32 vcc, 0, v35
	v_and_b32_e32 v35, 0x1000000, v65
	s_nop 0
	v_cndmask_b32_e32 v61, v237, v34, vcc
	v_sub_f32_e32 v34, v46, v139
	v_cmp_ne_u32_e32 vcc, 0, v35
	v_and_b32_e32 v35, 0x2000000, v65
	s_nop 0
	v_cndmask_b32_e32 v62, v237, v34, vcc
	v_sub_f32_e32 v34, v47, v139
	v_cmp_ne_u32_e32 vcc, 0, v35
	v_and_b32_e32 v35, 0x4000000, v65
	s_nop 0
	v_cndmask_b32_e32 v63, v237, v34, vcc
	v_sub_f32_e32 v34, v48, v139
	v_cmp_ne_u32_e32 vcc, 0, v35
	v_and_b32_e32 v35, 0x8000000, v65
	s_nop 0
	v_cndmask_b32_e32 v64, v237, v34, vcc
	v_sub_f32_e32 v34, v49, v139
	v_cmp_ne_u32_e32 vcc, 0, v35
	s_nop 1
	v_cndmask_b32_e32 v65, v237, v34, vcc
	v_lshrrev_b32_e32 v49, v134, v103
	v_and_b32_e32 v35, 1, v49
	s_waitcnt lgkmcnt(11)
	v_sub_f32_e32 v34, v174, v139
	v_cmp_eq_u32_e32 vcc, 1, v35
	v_and_b32_e32 v36, 2, v49
	s_waitcnt lgkmcnt(10)
	v_sub_f32_e32 v35, v176, v139
	v_cndmask_b32_e32 v34, v237, v34, vcc
	v_cmp_ne_u32_e32 vcc, 0, v36
	v_and_b32_e32 v37, 4, v49
	v_sub_f32_e32 v36, v177, v139
	v_cndmask_b32_e32 v35, v237, v35, vcc
	v_cmp_ne_u32_e32 vcc, 0, v37
	v_and_b32_e32 v38, 8, v49
	v_sub_f32_e32 v37, v175, v139
	v_cndmask_b32_e32 v36, v237, v36, vcc
	v_cmp_ne_u32_e32 vcc, 0, v38
	v_and_b32_e32 v39, 0x100, v49
	s_waitcnt lgkmcnt(9)
	v_sub_f32_e32 v38, v178, v139
	v_cndmask_b32_e32 v37, v237, v37, vcc
	v_cmp_ne_u32_e32 vcc, 0, v39
	v_and_b32_e32 v40, 0x200, v49
	v_sub_f32_e32 v39, v179, v139
	v_cndmask_b32_e32 v38, v237, v38, vcc
	v_cmp_ne_u32_e32 vcc, 0, v40
	v_and_b32_e32 v41, 0x400, v49
	s_waitcnt lgkmcnt(8)
	v_sub_f32_e32 v40, v180, v139
	v_cndmask_b32_e32 v39, v237, v39, vcc
	v_cmp_ne_u32_e32 vcc, 0, v41
	v_and_b32_e32 v42, 0x800, v49
	v_sub_f32_e32 v41, v181, v139
	v_cndmask_b32_e32 v40, v237, v40, vcc
	v_cmp_ne_u32_e32 vcc, 0, v42
	v_and_b32_e32 v43, 0x10000, v49
	s_waitcnt lgkmcnt(7)
	v_sub_f32_e32 v42, v182, v139
	v_cndmask_b32_e32 v41, v237, v41, vcc
	v_cmp_ne_u32_e32 vcc, 0, v43
	v_and_b32_e32 v44, 0x20000, v49
	v_sub_f32_e32 v43, v183, v139
	v_cndmask_b32_e32 v42, v237, v42, vcc
	v_cmp_ne_u32_e32 vcc, 0, v44
	v_and_b32_e32 v45, 0x40000, v49
	s_waitcnt lgkmcnt(6)
	v_sub_f32_e32 v44, v184, v139
	v_cndmask_b32_e32 v43, v237, v43, vcc
	v_cmp_ne_u32_e32 vcc, 0, v45
	v_and_b32_e32 v46, 0x80000, v49
	v_sub_f32_e32 v45, v185, v139
	v_cndmask_b32_e32 v44, v237, v44, vcc
	v_cmp_ne_u32_e32 vcc, 0, v46
	v_and_b32_e32 v47, 0x1000000, v49
	s_waitcnt lgkmcnt(5)
	v_sub_f32_e32 v46, v188, v139
	v_cndmask_b32_e32 v45, v237, v45, vcc
	v_cmp_ne_u32_e32 vcc, 0, v47
	v_and_b32_e32 v48, 0x2000000, v49
	v_sub_f32_e32 v47, v189, v139
	v_cndmask_b32_e32 v46, v237, v46, vcc
	v_cmp_ne_u32_e32 vcc, 0, v48
	v_and_b32_e32 v102, 0x4000000, v49
	s_waitcnt lgkmcnt(4)
	v_sub_f32_e32 v48, v190, v139
	v_cndmask_b32_e32 v47, v237, v47, vcc
	v_cmp_ne_u32_e32 vcc, 0, v102
	v_and_b32_e32 v49, 0x8000000, v49
	v_sub_f32_e32 v102, v191, v139
	v_cndmask_b32_e32 v48, v237, v48, vcc
	v_cmp_ne_u32_e32 vcc, 0, v49
	s_nop 1
	v_cndmask_b32_e32 v49, v237, v102, vcc
	s_waitcnt lgkmcnt(3)
	s_nop 0
	v_mfma_f32_32x32x16_bf16 v[34:49], v[158:161], v[94:97], v[34:49]
	v_mfma_f32_32x32x16_bf16 v[50:65], v[142:145], v[94:97], v[50:65]
	s_waitcnt lgkmcnt(2)
	v_mfma_f32_32x32x16_bf16 v[34:49], v[162:165], v[90:93], v[34:49]
	v_mfma_f32_32x32x16_bf16 v[50:65], v[146:149], v[90:93], v[50:65]
	s_waitcnt lgkmcnt(1)
	v_mfma_f32_32x32x16_bf16 v[34:49], v[166:169], v[86:89], v[34:49]
	v_mfma_f32_32x32x16_bf16 v[50:65], v[150:153], v[86:89], v[50:65]
	s_waitcnt lgkmcnt(0)
	v_mfma_f32_32x32x16_bf16 v[34:49], v[170:173], v[82:85], v[34:49]
	v_mfma_f32_32x32x16_bf16 v[50:65], v[154:157], v[82:85], v[50:65]
	s_nop 11
	s_branch .Ljoin_qk_c0
; __device__ __forceinline__ int crowc(int r) { return (r & 3) + 8 * (r >> 2); }
; template <int D, int DV, bool TAB, bool BITS, int KT> ...
;     ...
;                 if (TAB) {
; #pragma unroll
;                     for (int r = 0; r < 16; ++r) p0[r] = tabL[tj + crowc(r)];
; #pragma unroll
;                     for (int r = 0; r < 16; ++r) p1[r] = tabL[tj + 32 + crowc(r)];
;                     __builtin_amdgcn_sched_barrier(0);
; #pragma unroll
;                     for (int r = 0; r < 16; ++r) { p0[r] -= mhat; p1[r] -= mhat; }
;                 } else {
; #pragma unroll
;                     for (int r = 0; r < 16; ++r) { p0[r] = nm; p1[r] = nm; }
;                 }
;                 if (BITS) {
; #pragma unroll
;                     for (int r = 0; r < 16; ++r) { const int off = crowc(r); if (!((w0 >> off) & 1u)) p0[r] = NEGV; if (!((w1 >> off) & 1u)) p1[r] = NEGV; } }
; #pragma unroll
;                 for (int k4 = 0; k4 < D / 16; k4 += KG) {
;                     bf16x8 ka[KG], kb[KG];
; #pragma unroll
;                     for (int kk = 0; kk < KG; ++kk) { ka[kk] = *(const bf16x8*)(Kl + r32 * KP + ((k4 + kk) * 16 + 8 * hi) * 2); kb[kk] = *(const bf16x8*)(Kl + (32 + r32) * KP + ((k4 + kk) * 16 + 8 * hi) * 2); }
;                     __builtin_amdgcn_sched_barrier(0);
; #pragma unroll
;                     for (int kk = 0; kk < KG; ++kk) { p0 = __builtin_amdgcn_mfma_f32_32x32x16_bf16(ka[kk], qf[k4 + kk], p0, 0, 0, 0); p1 = __builtin_amdgcn_mfma_f32_32x32x16_bf16(kb[kk], qf[k4 + kk], p1, 0, 0, 0); }
;                     __builtin_amdgcn_sched_barrier(0);
;                 }
.Lslow_qk_c1:
	ds_read2_b32 v[34:35], v138 offset0:64 offset1:67
	ds_read2_b32 v[36:37], v138 offset0:65 offset1:66
	ds_read2_b32 v[38:39], v138 offset0:72 offset1:73
	ds_read2_b32 v[40:41], v138 offset0:74 offset1:75
	ds_read2_b32 v[42:43], v138 offset0:80 offset1:81
	ds_read_b128 v[142:145], v141 offset:9216
	ds_read_b128 v[146:149], v141 offset:9248
	ds_read_b128 v[150:153], v141 offset:9280
	ds_read_b128 v[154:157], v141 offset:9312
	ds_read2_b32 v[44:45], v138 offset0:96 offset1:99
	ds_read2_b32 v[46:47], v138 offset0:82 offset1:83
	ds_read2_b32 v[48:49], v138 offset0:88 offset1:89
	ds_read2_b32 v[64:65], v138 offset0:90 offset1:91
	ds_read2_b32 v[102:103], v138 offset0:97 offset1:98
	ds_read2_b32 v[174:175], v138 offset0:104 offset1:105
	ds_read2_b32 v[176:177], v138 offset0:106 offset1:107
	ds_read2_b32 v[178:179], v138 offset0:112 offset1:113
	ds_read2_b32 v[180:181], v138 offset0:114 offset1:115
	ds_read2_b32 v[182:183], v138 offset0:120 offset1:121
	ds_read2_b32 v[184:185], v138 offset0:122 offset1:123
	ds_read_b128 v[158:161], v141 offset:13824
	ds_read_b128 v[162:165], v141 offset:13856
	ds_read_b128 v[166:169], v141 offset:13888
	ds_read_b128 v[170:173], v141 offset:13920
	v_lshrrev_b32_e32 v104, v134, v104
	v_and_b32_e32 v50, 1, v104
	s_waitcnt lgkmcnt(14)
	v_sub_f32_e32 v34, v34, v139
	v_cmp_eq_u32_e32 vcc, 1, v50
	s_nop 1
	v_cndmask_b32_e32 v50, v237, v34, vcc
	v_sub_f32_e32 v34, v36, v139
	v_and_b32_e32 v36, 2, v104
	v_cmp_ne_u32_e32 vcc, 0, v36
	v_and_b32_e32 v36, 4, v104
	s_nop 0
	v_cndmask_b32_e32 v51, v237, v34, vcc
	v_sub_f32_e32 v34, v37, v139
	v_cmp_ne_u32_e32 vcc, 0, v36
	s_nop 1
	v_cndmask_b32_e32 v52, v237, v34, vcc
	v_sub_f32_e32 v34, v35, v139
	v_and_b32_e32 v35, 8, v104
	v_cmp_ne_u32_e32 vcc, 0, v35
	v_and_b32_e32 v35, 0x100, v104
	s_nop 0
	v_cndmask_b32_e32 v53, v237, v34, vcc
	v_sub_f32_e32 v34, v38, v139
	v_cmp_ne_u32_e32 vcc, 0, v35
	v_and_b32_e32 v35, 0x200, v104
	s_nop 0
	v_cndmask_b32_e32 v54, v237, v34, vcc
	v_sub_f32_e32 v34, v39, v139
	v_cmp_ne_u32_e32 vcc, 0, v35
	v_and_b32_e32 v35, 0x400, v104
	s_nop 0
	v_cndmask_b32_e32 v55, v237, v34, vcc
	v_sub_f32_e32 v34, v40, v139
	v_cmp_ne_u32_e32 vcc, 0, v35
	v_and_b32_e32 v35, 0x800, v104
	s_nop 0
	v_cndmask_b32_e32 v56, v237, v34, vcc
	v_sub_f32_e32 v34, v41, v139
	v_cmp_ne_u32_e32 vcc, 0, v35
	v_and_b32_e32 v35, 0x10000, v104
	s_nop 0
	v_cndmask_b32_e32 v57, v237, v34, vcc
	v_sub_f32_e32 v34, v42, v139
	v_cmp_ne_u32_e32 vcc, 0, v35
	v_and_b32_e32 v35, 0x20000, v104
	s_nop 0
	v_cndmask_b32_e32 v58, v237, v34, vcc
	v_sub_f32_e32 v34, v43, v139
	v_cmp_ne_u32_e32 vcc, 0, v35
	v_and_b32_e32 v35, 0x40000, v104
	s_nop 0
	v_cndmask_b32_e32 v59, v237, v34, vcc
	s_waitcnt lgkmcnt(13)
	v_sub_f32_e32 v34, v46, v139
	v_cmp_ne_u32_e32 vcc, 0, v35
	v_and_b32_e32 v35, 0x80000, v104
	s_nop 0
	v_cndmask_b32_e32 v60, v237, v34, vcc
	v_sub_f32_e32 v34, v47, v139
	v_cmp_ne_u32_e32 vcc, 0, v35
	v_and_b32_e32 v35, 0x1000000, v104
	s_nop 0
	v_cndmask_b32_e32 v61, v237, v34, vcc
	s_waitcnt lgkmcnt(12)
	v_sub_f32_e32 v34, v48, v139
	v_cmp_ne_u32_e32 vcc, 0, v35
	v_and_b32_e32 v35, 0x2000000, v104
	s_nop 0
	v_cndmask_b32_e32 v62, v237, v34, vcc
	v_sub_f32_e32 v34, v49, v139
	v_cmp_ne_u32_e32 vcc, 0, v35
	v_and_b32_e32 v35, 0x4000000, v104
	s_nop 0
	v_cndmask_b32_e32 v63, v237, v34, vcc
	s_waitcnt lgkmcnt(11)
	v_sub_f32_e32 v34, v64, v139
	v_cmp_ne_u32_e32 vcc, 0, v35
	v_and_b32_e32 v35, 0x8000000, v104
	s_nop 0
	v_cndmask_b32_e32 v64, v237, v34, vcc
	v_sub_f32_e32 v34, v65, v139
	v_cmp_ne_u32_e32 vcc, 0, v35
	s_nop 1
	v_cndmask_b32_e32 v65, v237, v34, vcc
	v_lshrrev_b32_e32 v49, v134, v105
	v_and_b32_e32 v35, 1, v49
	v_sub_f32_e32 v34, v44, v139
	v_cmp_eq_u32_e32 vcc, 1, v35
	v_and_b32_e32 v36, 2, v49
	s_waitcnt lgkmcnt(10)
	v_sub_f32_e32 v35, v102, v139
	v_cndmask_b32_e32 v34, v237, v34, vcc
	v_cmp_ne_u32_e32 vcc, 0, v36
	v_and_b32_e32 v37, 4, v49
	v_sub_f32_e32 v36, v103, v139
	v_cndmask_b32_e32 v35, v237, v35, vcc
	v_cmp_ne_u32_e32 vcc, 0, v37
	v_and_b32_e32 v38, 8, v49
	v_sub_f32_e32 v37, v45, v139
	v_cndmask_b32_e32 v36, v237, v36, vcc
	v_cmp_ne_u32_e32 vcc, 0, v38
	v_and_b32_e32 v39, 0x100, v49
	s_waitcnt lgkmcnt(9)
	v_sub_f32_e32 v38, v174, v139
	v_cndmask_b32_e32 v37, v237, v37, vcc
	v_cmp_ne_u32_e32 vcc, 0, v39
	v_and_b32_e32 v40, 0x200, v49
	v_sub_f32_e32 v39, v175, v139
	v_cndmask_b32_e32 v38, v237, v38, vcc
	v_cmp_ne_u32_e32 vcc, 0, v40
	v_and_b32_e32 v41, 0x400, v49
	s_waitcnt lgkmcnt(8)
	v_sub_f32_e32 v40, v176, v139
	v_cndmask_b32_e32 v39, v237, v39, vcc
	v_cmp_ne_u32_e32 vcc, 0, v41
	v_and_b32_e32 v42, 0x800, v49
	v_sub_f32_e32 v41, v177, v139
	v_cndmask_b32_e32 v40, v237, v40, vcc
	v_cmp_ne_u32_e32 vcc, 0, v42
	v_and_b32_e32 v43, 0x10000, v49
	s_waitcnt lgkmcnt(7)
	v_sub_f32_e32 v42, v178, v139
	v_cndmask_b32_e32 v41, v237, v41, vcc
	v_cmp_ne_u32_e32 vcc, 0, v43
	v_and_b32_e32 v44, 0x20000, v49
	v_sub_f32_e32 v43, v179, v139
	v_cndmask_b32_e32 v42, v237, v42, vcc
	v_cmp_ne_u32_e32 vcc, 0, v44
	v_and_b32_e32 v45, 0x40000, v49
	s_waitcnt lgkmcnt(6)
	v_sub_f32_e32 v44, v180, v139
	v_cndmask_b32_e32 v43, v237, v43, vcc
	v_cmp_ne_u32_e32 vcc, 0, v45
	v_and_b32_e32 v46, 0x80000, v49
	v_sub_f32_e32 v45, v181, v139
	v_cndmask_b32_e32 v44, v237, v44, vcc
	v_cmp_ne_u32_e32 vcc, 0, v46
	v_and_b32_e32 v47, 0x1000000, v49
	s_waitcnt lgkmcnt(5)
	v_sub_f32_e32 v46, v182, v139
	v_cndmask_b32_e32 v45, v237, v45, vcc
	v_cmp_ne_u32_e32 vcc, 0, v47
	v_and_b32_e32 v48, 0x2000000, v49
	v_sub_f32_e32 v47, v183, v139
	v_cndmask_b32_e32 v46, v237, v46, vcc
	v_cmp_ne_u32_e32 vcc, 0, v48
	v_and_b32_e32 v102, 0x4000000, v49
	s_waitcnt lgkmcnt(4)
	v_sub_f32_e32 v48, v184, v139
	v_cndmask_b32_e32 v47, v237, v47, vcc
	v_cmp_ne_u32_e32 vcc, 0, v102
	v_and_b32_e32 v49, 0x8000000, v49
	v_sub_f32_e32 v102, v185, v139
	v_cndmask_b32_e32 v48, v237, v48, vcc
	v_cmp_ne_u32_e32 vcc, 0, v49
	s_nop 1
	v_cndmask_b32_e32 v49, v237, v102, vcc
	s_waitcnt lgkmcnt(3)
	s_nop 0
	v_mfma_f32_32x32x16_bf16 v[34:49], v[158:161], v[94:97], v[34:49]
	v_mfma_f32_32x32x16_bf16 v[50:65], v[142:145], v[94:97], v[50:65]
	s_waitcnt lgkmcnt(2)
	v_mfma_f32_32x32x16_bf16 v[34:49], v[162:165], v[90:93], v[34:49]
	v_mfma_f32_32x32x16_bf16 v[50:65], v[146:149], v[90:93], v[50:65]
	s_waitcnt lgkmcnt(1)
	v_mfma_f32_32x32x16_bf16 v[34:49], v[166:169], v[86:89], v[34:49]
	v_mfma_f32_32x32x16_bf16 v[50:65], v[150:153], v[86:89], v[50:65]
	s_waitcnt lgkmcnt(0)
	v_mfma_f32_32x32x16_bf16 v[34:49], v[170:173], v[82:85], v[34:49]
	v_mfma_f32_32x32x16_bf16 v[50:65], v[154:157], v[82:85], v[50:65]
	s_nop 11
	s_branch .Ljoin_qk_c1
; __device__ __forceinline__ float swap32_max(float v) { auto rr = __builtin_amdgcn_permlane32_swap(__float_as_uint(v), __float_as_uint(v), false, false); return fmaxf(__uint_as_float(rr[0]), __uint_as_float(rr[1])); }
; template <int D, int DV, bool TAB, bool BITS, int KT> ...
;     ...
;             mx = swap32_max(mx);
;             if (__any(mx > 8.0f)) {
;                 const float dl = fmaxf(mx, 0.f); mhat += dl;
; #pragma unroll
;                 for (int r = 0; r < 16; ++r) { p0[r] -= dl; p1[r] -= dl; }
;                 const float alpha = __builtin_amdgcn_exp2f(-dl); l_run *= alpha;
;                 if (hi == 0) wsf[r32] = alpha;
;                 __builtin_amdgcn_fence(__ATOMIC_RELEASE, "wavefront"); __builtin_amdgcn_wave_barrier();
; #pragma unroll
;                 for (int j = 0; j < 4; ++j) { const f32x4 a4 = *(const f32x4*)(wsf + 8 * j + 4 * hi);
; #pragma unroll
;                     for (int dt = 0; dt < DV / 32; ++dt) { o[dt][4 * j + 0] *= a4[0]; o[dt][4 * j + 1] *= a4[1]; o[dt][4 * j + 2] *= a4[2]; o[dt][4 * j + 3] *= a4[3]; } }
;                 __builtin_amdgcn_fence(__ATOMIC_RELEASE, "wavefront"); __builtin_amdgcn_wave_barrier();
;             }
.Lrare_6:
	s_nop 11
	v_mov_b32_e32 v103, v34
	s_nop 1
	v_permlane32_swap_b32_e32 v34, v103
	v_add_f32_e32 v102, v34, v103
	v_log_f32_e32 v102, v102
	s_nop 0
	v_max_f32_e32 v102, v102, v102
	v_max_f32_e32 v102, 0, v102
	v_exp_f32_e64 v103, -v102
	s_and_saveexec_b64 s[70:71], s[6:7]
	ds_write_b32 v121, v103
	s_or_b64 exec, exec, s[70:71]
	ds_read_b128 v[142:145], v136
	ds_read_b128 v[146:149], v136 offset:32
	ds_read_b128 v[150:153], v136 offset:64
	ds_read_b128 v[154:157], v136 offset:96
	v_add_f32_e32 v139, v139, v102
	s_mov_b32 s100, 1
	v_mul_f32_e32 v133, v133, v103
	s_waitcnt lgkmcnt(0)
	v_pk_mul_f32 v[16:17], v[16:17], v[156:157]
	v_pk_mul_f32 v[12:13], v[12:13], v[152:153]
	v_pk_mul_f32 v[8:9], v[8:9], v[148:149]
	v_pk_mul_f32 v[4:5], v[4:5], v[144:145]
	v_pk_mul_f32 v[32:33], v[32:33], v[156:157]
	v_pk_mul_f32 v[28:29], v[28:29], v[152:153]
	v_pk_mul_f32 v[24:25], v[24:25], v[148:149]
	v_pk_mul_f32 v[20:21], v[20:21], v[144:145]
	v_pk_mul_f32 v[14:15], v[14:15], v[154:155]
	v_pk_mul_f32 v[10:11], v[10:11], v[150:151]
	v_pk_mul_f32 v[6:7], v[6:7], v[146:147]
	v_pk_mul_f32 v[2:3], v[2:3], v[142:143]
	v_pk_mul_f32 v[30:31], v[30:31], v[154:155]
	v_pk_mul_f32 v[26:27], v[26:27], v[150:151]
	v_pk_mul_f32 v[22:23], v[22:23], v[146:147]
	v_pk_mul_f32 v[18:19], v[18:19], v[142:143]
	s_branch .Lback_6
.Lrare_7:
	s_nop 11
	v_mov_b32_e32 v103, v34
	s_nop 1
	v_permlane32_swap_b32_e32 v34, v103
	v_add_f32_e32 v102, v34, v103
	v_log_f32_e32 v102, v102
	s_nop 0
	v_max_f32_e32 v102, v102, v102
	v_max_f32_e32 v102, 0, v102
	v_exp_f32_e64 v103, -v102
	s_and_saveexec_b64 s[70:71], s[6:7]
	ds_write_b32 v121, v103
	s_or_b64 exec, exec, s[70:71]
	v_add_f32_e32 v139, v139, v102
	s_mov_b32 s100, 1
	v_mul_f32_e32 v133, v133, v103
	ds_read_b128 v[102:105], v136
	ds_read_b128 v[142:145], v136 offset:32
	ds_read_b128 v[146:149], v136 offset:64
	ds_read_b128 v[150:153], v136 offset:96
	s_waitcnt lgkmcnt(3)
	v_pk_mul_f32 v[4:5], v[4:5], v[104:105]
	s_waitcnt lgkmcnt(2)
	v_pk_mul_f32 v[8:9], v[8:9], v[144:145]
	s_waitcnt lgkmcnt(1)
	v_pk_mul_f32 v[12:13], v[12:13], v[148:149]
	s_waitcnt lgkmcnt(0)
	v_pk_mul_f32 v[16:17], v[16:17], v[152:153]
	v_pk_mul_f32 v[32:33], v[32:33], v[152:153]
	v_pk_mul_f32 v[28:29], v[28:29], v[148:149]
	v_pk_mul_f32 v[24:25], v[24:25], v[144:145]
	v_pk_mul_f32 v[20:21], v[20:21], v[104:105]
	v_pk_mul_f32 v[14:15], v[14:15], v[150:151]
	v_pk_mul_f32 v[10:11], v[10:11], v[146:147]
	v_pk_mul_f32 v[6:7], v[6:7], v[142:143]
	v_pk_mul_f32 v[2:3], v[2:3], v[102:103]
	v_pk_mul_f32 v[30:31], v[30:31], v[150:151]
	v_pk_mul_f32 v[26:27], v[26:27], v[146:147]
	v_pk_mul_f32 v[22:23], v[22:23], v[142:143]
	v_pk_mul_f32 v[18:19], v[18:19], v[102:103]
	s_branch .Lback_7

; __device__ __forceinline__ unsigned cvtpk(float lo, float hi) { f32x2_t v = {lo, hi}; bf16x2_t b = __builtin_convertvector(v, bf16x2_t); return __builtin_bit_cast(unsigned, b); }
; template <int D, int DV, bool TAB, bool BITS, int KT> ...
;     ...
;     int tid_o = threadIdx.x; asm volatile("" : "+v"(tid_o));
;     const int tid = tid_o, lane = tid & 63, wid = __builtin_amdgcn_readfirstlane(tid >> 6), r32 = lane & 31, hi = lane >> 5;
;     float* tabL = (float*)(lds + TOFF); float* wsf = (float*)(lds + WOFF) + wid * 64;
;     if (TAB && ltab) { for (int i = tid; i < TABN / 4; i += 512) ((f32x4*)tabL)[i] = ((const f32x4*)tabg)[i]; }
;     bf16x8 qf[D / 16];
;     { const bf16_t* qrow = Qp + (size_t)(32 * wid + r32) * ldq + 8 * hi;
; #pragma unroll
;       for (int kk = 0; kk < D / 16; ++kk) { const u32x4v raw = *(const u32x4v*)(qrow + kk * 16); u32x4v sc4;
; #pragma unroll
;           for (int e = 0; e < 4; ++e) { const float lo = __builtin_bit_cast(float, raw[e] << 16) * c2, hh = __builtin_bit_cast(float, raw[e] & 0xffff0000u) * c2; sc4[e] = cvtpk(lo, hh); }
;           qf[kk] = __builtin_bit_cast(bf16x8, sc4); } }
; #pragma unroll
;     for (int dt = 0; dt < DV / 32; ++dt)
; #pragma unroll
;         for (int r = 0; r < 16; ++r) o[dt][r] = 0.f;
;     float mhat = 0.f, l_run = 0.f;
;     const int qpos = q0 + 32 * wid + r32, qw_lo = q0 + 32 * wid, qw_hi = qw_lo + 31;
;     u32x4v kreg[NKC], vreg[NVC];
;     ...
;     AT_LOAD(t_lo); AT_STORE(0);
;     unsigned wq[NBW], wn[NBW];
;     const unsigned* bprow = BITS ? bitsp + (size_t)(32 * wid + r32) * 128 : nullptr;
; #pragma unroll
;     for (int i = 0; i < NBW; ++i) { wq[i] = 0xffffffffu; wn[i] = 0xffffffffu; if (BITS) wq[i] = bprow[NBW * t_lo + i]; }
;     __syncthreads();
; __device__ __forceinline__ void unitC(unsigned char* lds, const MixCtx& c, int b, int h, int qb, bool ltab) {
;     const int q0 = qb * 256; const size_t tokb = (size_t)b * SEQ; const int t_hi = (q0 + 256) / 128;
;     f32x16 o[2];
;     attn_pass<64, 64, true, true, 128>(lds, c.P + (tokb + q0) * PW + P_CQ + h * 64, PW, c.P + tokb * PW + P_CK + h * 64, PW, c.VT + (size_t)(V_C + h * 64) * MTOK + tokb, MTOK,
;                                   c.tabs + (8 + h) * TABN, c.bits + (tokb + q0) * 128, q0, 0, t_hi, 1 << 24, 0.125f * LOG2E, o, ltab);
.LBB0_948:
	s_or_b64 exec, exec, s[0:1]
	s_ashr_i32 s5, s25, 6
	s_bfe_u32 s0, s25, 0x20006
	s_and_b32 s6, s5, 0xfffffc
	s_or_b32 s5, s5, 3
	s_bfe_u32 s4, s25, 0x40002
	s_and_b32 s1, s25, 0x100
	s_sub_i32 s5, s5, s0
	s_or_b32 s0, s6, s0
	s_cmp_eq_u32 s1, 0
	s_cselect_b32 s0, s0, s5
	s_lshl_b32 s9, s0, 8
	s_add_i32 s1, s9, 0x100
	s_lshl_b32 s0, s4, 12
	s_ashr_i32 s62, s1, 7
	s_ashr_i32 s1, s9, 31
	s_add_u32 s0, s0, s9
	s_addc_u32 s1, 0, s1
	s_mul_i32 s5, s1, 0x1600
	s_mul_hi_u32 s6, s0, 0x1600
	s_add_i32 s6, s6, s5
	s_mul_i32 s5, s0, 0x1600
	s_add_u32 s5, s46, s5
	s_addc_u32 s6, s47, s6
	s_lshl_b32 s7, s35, 7
	s_add_u32 s52, s5, s7
	s_addc_u32 s53, s6, 0
	s_mul_i32 s5, s4, 0x1600000
	s_add_u32 s5, s46, s5
	s_addc_u32 s6, s47, 0
	s_add_u32 s10, s5, s7
	s_addc_u32 s11, s6, 0
	s_lshl_b32 s5, s35, 23
	s_add_u32 s5, s18, s5
	s_addc_u32 s6, s19, 0
	s_lshl_b32 s4, s4, 13
	s_add_u32 s4, s5, s4
	s_addc_u32 s5, s6, 0
	s_add_u32 s4, s4, 0x6000000
	s_addc_u32 s5, s5, 0
	s_lshl_b64 s[6:7], s[0:1], 9
	v_lshrrev_b32_e32 v3, 29, v23
	s_add_u32 s6, s86, s6
	v_add_u32_e32 v3, v22, v3
	s_addc_u32 s7, s87, s7
	s_ashr_i32 s12, s8, 1
	v_ashrrev_i32_e32 v122, 3, v3
	v_and_b32_e32 v3, -8, v3
	v_mov_b32_e32 v0, s12
	s_movk_i32 s13, 0xffe0
	v_sub_u32_e32 v28, v22, v3
	v_bfe_u32 v120, v22, 5, 1
	v_bfi_b32 v2, s13, v0, v22
	v_mov_b64_e32 v[4:5], s[52:53]
	v_mov_b64_e32 v[6:7], s[10:11]
	v_lshlrev_b32_e32 v18, 3, v28
	v_mad_i64_i32 v[4:5], s[52:53], v2, s37, v[4:5]
	v_lshlrev_b32_e32 v0, 4, v120
	v_mad_i64_i32 v[8:9], s[52:53], v122, s37, v[6:7]
	v_ashrrev_i32_e32 v19, 31, v18
	v_add_u32_e32 v3, 0x200, v22
	v_lshl_add_u64 v[4:5], v[4:5], 0, v[0:1]
	v_lshl_add_u64 v[8:9], v[18:19], 1, v[8:9]
	v_ashrrev_i32_e32 v14, 31, v3
	global_load_dwordx4 v[10:13], v[4:5], off offset:3168
	global_load_dwordx4 v[66:69], v[8:9], off offset:3584
	v_lshrrev_b32_e32 v8, 29, v14
	v_add_u32_e32 v8, v3, v8
	v_ashrrev_i32_e32 v123, 3, v8
	v_and_b32_e32 v8, -8, v8
	v_sub_u32_e32 v29, v3, v8
	v_lshrrev_b32_e32 v8, 28, v23
	v_add_u32_e32 v8, v22, v8
	v_ashrrev_i32_e32 v24, 4, v8
	v_and_b32_e32 v8, -16, v8
	v_lshlrev_b32_e32 v20, 3, v29
	v_sub_u32_e32 v23, v22, v8
	v_ashrrev_i32_e32 v25, 31, v24
	v_mad_i64_i32 v[6:7], s[52:53], v123, s37, v[6:7]
	v_ashrrev_i32_e32 v21, 31, v20
	v_lshlrev_b64 v[106:107], 17, v[24:25]
	v_lshlrev_b32_e32 v108, 3, v23
	v_lshl_add_u64 v[6:7], v[20:21], 1, v[6:7]
	v_lshl_add_u64 v[8:9], s[4:5], 0, v[106:107]
	v_ashrrev_i32_e32 v109, 31, v108
	v_lshl_add_u64 v[8:9], v[108:109], 1, v[8:9]
	global_load_dwordx4 v[70:73], v[6:7], off offset:3584
	global_load_dwordx4 v[74:77], v[8:9], off
	v_lshrrev_b32_e32 v6, 28, v14
	v_add_u32_e32 v6, v3, v6
	v_ashrrev_i32_e32 v26, 4, v6
	v_and_b32_e32 v6, -16, v6
	v_sub_u32_e32 v25, v3, v6
	v_ashrrev_i32_e32 v27, 31, v26
	v_lshlrev_b64 v[110:111], 17, v[26:27]
	v_lshlrev_b32_e32 v112, 3, v25
	v_lshl_add_u64 v[6:7], s[4:5], 0, v[110:111]
	v_ashrrev_i32_e32 v113, 31, v112
	v_ashrrev_i32_e32 v3, 31, v2
	v_lshl_add_u64 v[6:7], v[112:113], 1, v[6:7]
	v_lshlrev_b64 v[2:3], 9, v[2:3]
	global_load_dwordx4 v[78:81], v[6:7], off
	s_nop 0
	global_load_dwordx4 v[6:9], v[4:5], off offset:3104
	global_load_dwordx4 v[14:17], v[4:5], off offset:3136
	v_lshl_add_u64 v[114:115], s[6:7], 0, v[2:3]
	global_load_dwordx4 v[2:5], v[4:5], off offset:3072
	s_nop 0
	global_load_dwordx4 v[102:105], v[114:115], off
	s_and_b32 s6, s8, 0x3fffffc0
	s_lshl_b32 s6, s6, 2
	s_add_i32 s63, s6, 0
	s_movk_i32 s6, 0x90
	v_mul_lo_u32 v124, v122, s6
	v_lshlrev_b32_e32 v125, 4, v28
	v_mul_lo_u32 v128, v24, s91
	v_add3_u32 v27, 0, v124, v125
	v_mul_lo_u32 v126, v123, s6
	v_lshlrev_b32_e32 v127, 4, v29
	v_add_u32_e32 v24, 0, v128
	v_lshlrev_b32_e32 v129, 4, v23
	v_add3_u32 v23, v24, v129, s92
	v_mul_lo_u32 v130, v26, s91
	v_and_b32_e32 v22, 31, v22
	s_add_i32 s63, s63, 0x15800
	v_lshlrev_b32_e32 v131, 4, v25
	s_mov_b32 s72, 0
	s_cmp_lt_i32 s62, 1
	v_cmp_eq_u32_e64 s[6:7], 0, v120
	v_lshl_add_u32 v121, v22, 2, s63
	s_waitcnt vmcnt(7)
	ds_write_b128 v27, v[66:69]
	v_add3_u32 v27, 0, v126, v127
	s_waitcnt vmcnt(6)
	ds_write_b128 v27, v[70:73]
	s_waitcnt vmcnt(5)
	ds_write2_b64 v23, v[74:75], v[76:77] offset1:1
	v_add_u32_e32 v23, 0, v130
	v_add3_u32 v23, v23, v131, s92
	s_waitcnt vmcnt(4)
	ds_write2_b64 v23, v[78:79], v[80:81] offset1:1
	s_waitcnt lgkmcnt(0)
	s_barrier
; __device__ __forceinline__ unsigned cvtpk(float lo, float hi) { f32x2_t v = {lo, hi}; bf16x2_t b = __builtin_convertvector(v, bf16x2_t); return __builtin_bit_cast(unsigned, b); }
; template <int D, int DV, bool TAB, bool BITS, int KT> ...
;     ...
;     bf16x8 qf[D / 16];
;     { const bf16_t* qrow = Qp + (size_t)(32 * wid + r32) * ldq + 8 * hi;
; #pragma unroll
;       for (int kk = 0; kk < D / 16; ++kk) { const u32x4v raw = *(const u32x4v*)(qrow + kk * 16); u32x4v sc4;
; #pragma unroll
;           for (int e = 0; e < 4; ++e) { const float lo = __builtin_bit_cast(float, raw[e] << 16) * c2, hh = __builtin_bit_cast(float, raw[e] & 0xffff0000u) * c2; sc4[e] = cvtpk(lo, hh); }
;           qf[kk] = __builtin_bit_cast(bf16x8, sc4); } }
; #pragma unroll
;     for (int dt = 0; dt < DV / 32; ++dt)
; #pragma unroll
;         for (int r = 0; r < 16; ++r) o[dt][r] = 0.f;
;     float mhat = 0.f, l_run = 0.f;
;     const int qpos = q0 + 32 * wid + r32, qw_lo = q0 + 32 * wid, qw_hi = qw_lo + 31;
;     u32x4v kreg[NKC], vreg[NVC];
;     ...
;     AT_LOAD(t_lo); AT_STORE(0);
	s_cbranch_scc1 .LBB0_968
	v_lshlrev_b32_e32 v24, 16, v10
	v_and_b32_e32 v25, 0xffff0000, v10
	v_lshlrev_b32_e32 v10, 16, v11
	v_and_b32_e32 v11, 0xffff0000, v11
	v_pk_mul_f32 v[10:11], v[10:11], s[58:59] op_sel_hi:[1,0]
	s_and_b32 s8, s12, 0xffffffe0
	v_cvt_pk_bf16_f32 v83, v10, v11
	v_lshlrev_b32_e32 v10, 16, v12
	v_and_b32_e32 v11, 0xffff0000, v12
	v_pk_mul_f32 v[10:11], v[10:11], s[58:59] op_sel_hi:[1,0]
	s_add_i32 s8, s8, s9
	v_cvt_pk_bf16_f32 v84, v10, v11
	v_lshlrev_b32_e32 v10, 16, v13
	v_and_b32_e32 v11, 0xffff0000, v13
	v_pk_mul_f32 v[10:11], v[10:11], s[58:59] op_sel_hi:[1,0]
	v_lshlrev_b32_e32 v134, 2, v120
	v_cvt_pk_bf16_f32 v85, v10, v11
	s_waitcnt vmcnt(2)
	v_lshlrev_b32_e32 v10, 16, v14
	v_and_b32_e32 v11, 0xffff0000, v14
	v_pk_mul_f32 v[10:11], v[10:11], s[58:59] op_sel_hi:[1,0]
	s_movk_i32 s9, 0xfff
	v_cvt_pk_bf16_f32 v86, v10, v11
	v_lshlrev_b32_e32 v10, 16, v15
	v_and_b32_e32 v11, 0xffff0000, v15
	v_pk_mul_f32 v[10:11], v[10:11], s[58:59] op_sel_hi:[1,0]
	v_lshlrev_b32_e32 v23, 3, v120
	v_cvt_pk_bf16_f32 v87, v10, v11
	v_lshlrev_b32_e32 v10, 16, v16
	v_and_b32_e32 v11, 0xffff0000, v16
	v_pk_mul_f32 v[10:11], v[10:11], s[58:59] op_sel_hi:[1,0]
	v_pk_mul_f32 v[24:25], v[24:25], s[58:59] op_sel_hi:[1,0]
	v_cvt_pk_bf16_f32 v88, v10, v11
	v_lshlrev_b32_e32 v10, 16, v17
	v_and_b32_e32 v11, 0xffff0000, v17
	v_pk_mul_f32 v[10:11], v[10:11], s[58:59] op_sel_hi:[1,0]
	v_mov_b32_e32 v187, v186
	v_cvt_pk_bf16_f32 v89, v10, v11
	v_lshlrev_b32_e32 v10, 16, v6
	v_and_b32_e32 v11, 0xffff0000, v6
	v_lshlrev_b32_e32 v6, 16, v7
	v_and_b32_e32 v7, 0xffff0000, v7
	v_pk_mul_f32 v[6:7], v[6:7], s[58:59] op_sel_hi:[1,0]
	v_pk_mul_f32 v[10:11], v[10:11], s[58:59] op_sel_hi:[1,0]
	v_cvt_pk_bf16_f32 v91, v6, v7
	v_lshlrev_b32_e32 v6, 16, v8
	v_and_b32_e32 v7, 0xffff0000, v8
	v_pk_mul_f32 v[6:7], v[6:7], s[58:59] op_sel_hi:[1,0]
	v_mov_b32_e32 v139, 0
	s_mov_b32 s100, 0
	v_cvt_pk_bf16_f32 v92, v6, v7
	v_lshlrev_b32_e32 v6, 16, v9
	v_and_b32_e32 v7, 0xffff0000, v9
	v_pk_mul_f32 v[6:7], v[6:7], s[58:59] op_sel_hi:[1,0]
	s_or_b32 s73, s8, 31
	v_cvt_pk_bf16_f32 v93, v6, v7
	s_waitcnt vmcnt(1)
	v_lshlrev_b32_e32 v6, 16, v2
	v_and_b32_e32 v7, 0xffff0000, v2
	v_lshlrev_b32_e32 v2, 16, v3
	v_and_b32_e32 v3, 0xffff0000, v3
	v_pk_mul_f32 v[2:3], v[2:3], s[58:59] op_sel_hi:[1,0]
	v_pk_mul_f32 v[6:7], v[6:7], s[58:59] op_sel_hi:[1,0]
	v_cvt_pk_bf16_f32 v95, v2, v3
	v_lshlrev_b32_e32 v2, 16, v4
	v_and_b32_e32 v3, 0xffff0000, v4
	v_pk_mul_f32 v[2:3], v[2:3], s[58:59] op_sel_hi:[1,0]
	v_add_u32_e32 v132, 0, v23
	v_cvt_pk_bf16_f32 v96, v2, v3
	v_lshlrev_b32_e32 v2, 16, v5
	v_and_b32_e32 v3, 0xffff0000, v5
	v_pk_mul_f32 v[2:3], v[2:3], s[58:59] op_sel_hi:[1,0]
	v_cvt_pk_bf16_f32 v82, v24, v25
	v_cvt_pk_bf16_f32 v97, v2, v3
	v_xad_u32 v2, v22, s9, v134
	v_subrev_u32_e32 v2, s8, v2
	v_readlane_b32 s9, v255, 16
	v_cvt_pk_bf16_f32 v90, v10, v11
	v_cvt_pk_bf16_f32 v94, v6, v7
	s_add_i32 s74, s8, 0xff000000
	v_mul_u32_u24_e32 v135, 0x90, v22
	s_mov_b32 s8, 4
	v_add_u32_e32 v136, s63, v0
	v_lshl_add_u64 v[116:117], v[18:19], 1, s[10:11]
	v_lshl_add_u64 v[118:119], v[20:21], 1, s[10:11]
	v_mul_u32_u24_e32 v137, 0x108, v22
	v_lshl_add_u32 v138, v2, 2, s9
	s_movk_i32 s64, 0x80
	v_mov_b32_e32 v133, 0
	s_mov_b32 s75, 0
	v_mov_b64_e32 v[100:101], v[186:187]
	v_mov_b64_e32 v[98:99], v[186:187]
	v_mov_b32_e32 v18, 0
	v_mov_b32_e32 v19, v139
	v_mov_b32_e32 v20, v139
	v_mov_b32_e32 v21, v139
	v_mov_b32_e32 v22, v139
	v_mov_b32_e32 v23, v139
	v_mov_b32_e32 v24, v139
	v_mov_b32_e32 v25, v139
	v_mov_b32_e32 v26, v139
	v_mov_b32_e32 v27, v139
	v_mov_b32_e32 v28, v139
	v_mov_b32_e32 v29, v139
	v_mov_b32_e32 v30, v139
	v_mov_b32_e32 v31, v139
	v_mov_b32_e32 v32, v139
	v_mov_b32_e32 v33, v139
	v_mov_b32_e32 v2, v139
	v_mov_b32_e32 v3, v139
	v_mov_b32_e32 v4, v139
	v_mov_b32_e32 v5, v139
	v_mov_b32_e32 v6, v139
	v_mov_b32_e32 v7, v139
	v_mov_b32_e32 v8, v139
	v_mov_b32_e32 v9, v139
	v_mov_b32_e32 v10, v139
	v_mov_b32_e32 v11, v139
	v_mov_b32_e32 v12, v139
	v_mov_b32_e32 v13, v139
	v_mov_b32_e32 v14, v139
	v_mov_b32_e32 v15, v139
	v_mov_b32_e32 v16, v139
	v_mov_b32_e32 v17, v139
	s_waitcnt vmcnt(0)

; template <int D, int DV, bool TAB, bool BITS, int KT> ...
;     ...
;         for (int sub = 0; sub < NSUB; ++sub) {
;         const int k0 = t * KT + sub * 64;
;         bool active = true;
;         if (TAB) active = (k0 <= qw_hi) && (k0 + 63 >= qw_lo - win);
;         if (active) {
;             const unsigned char* Kl = lds + KOFF + cur * KBUF + sub * 64 * KP; const unsigned char* Vl = lds + VOFF + cur * VBUF + sub * 128;
;             f32x16 p0, p1;
;             unsigned w0 = 0xffffffffu, w1 = 0xffffffffu;
;             if (BITS) { w0 = wq[2 * sub] >> (4 * hi); w1 = wq[2 * sub + 1] >> (4 * hi); }
;             const float nm = -mhat;
;             const int tj = TABN - 1 - TABOFF - qpos + k0 + 4 * hi;
;             constexpr int KG = (D > 64) ? 2 : 4;
;             if (D == 64) {
;                 bf16x8 ka[4], kb[4];
;                 if (TAB) {
; #pragma unroll
;                     for (int r = 0; r < 16; ++r) p0[r] = tabL[tj + crowc(r)]; }
; #pragma unroll
;                 for (int kk = 0; kk < 4; ++kk) ka[kk] = *(const bf16x8*)(Kl + r32 * KP + (kk * 16 + 8 * hi) * 2);
;                 if (TAB) {
; #pragma unroll
;                     for (int r = 0; r < 16; ++r) p1[r] = tabL[tj + 32 + crowc(r)]; }
; #pragma unroll
;                 for (int kk = 0; kk < 4; ++kk) kb[kk] = *(const bf16x8*)(Kl + (32 + r32) * KP + (kk * 16 + 8 * hi) * 2);
;                 __builtin_amdgcn_sched_barrier(0);
; #pragma unroll
;                 for (int r = 0; r < 16; ++r) { if (TAB) p0[r] -= mhat; else p0[r] = nm; if (BITS) { if (!((w0 >> crowc(r)) & 1u)) p0[r] = NEGV; } }
;                 __builtin_amdgcn_sched_barrier(0);
; #pragma unroll
;                 for (int kk = 0; kk < 4; ++kk) p0 = __builtin_amdgcn_mfma_f32_32x32x16_bf16(ka[kk], qf[kk], p0, 0, 0, 0);
; #pragma unroll
;                 for (int r = 0; r < 16; ++r) { if (TAB) p1[r] -= mhat; else p1[r] = nm; if (BITS) { if (!((w1 >> crowc(r)) & 1u)) p1[r] = NEGV; } }
;                 __builtin_amdgcn_sched_barrier(0);
; #pragma unroll
;                 for (int kk = 0; kk < 4; ++kk) p1 = __builtin_amdgcn_mfma_f32_32x32x16_bf16(kb[kk], qf[kk], p1, 0, 0, 0);
;                 __builtin_amdgcn_sched_barrier(0);
;             } else {
;                 if (TAB) {
; #pragma unroll
;                     for (int r = 0; r < 16; ++r) p0[r] = tabL[tj + crowc(r)];
; #pragma unroll
.LBB0_952:
	s_mul_i32 s12, s72, 0x4800
	s_add_i32 s9, s64, 0xffffff80
	s_add_i32 s50, s12, 0
	s_mul_i32 s12, s72, 0x4200
	s_cmp_le_i32 s9, s73
	v_add_u32_e32 v140, s12, v132
	s_cselect_b64 s[12:13], -1, 0
	s_add_i32 s9, s64, 0xffffffbf
	s_cmp_ge_i32 s9, s74
	s_cselect_b64 s[52:53], -1, 0
	s_and_b64 s[12:13], s[12:13], s[52:53]
	s_and_b64 vcc, exec, s[12:13]
	v_add3_u32 v141, s50, v135, v0
	s_cbranch_vccz .LBB0_958
	s_cmp_lg_u32 s100, 0
	s_cbranch_scc1 .Lslow_qk_c0
	ds_read2_b32 v[50:51], v138 offset1:1
	ds_read2_b32 v[52:53], v138 offset0:2 offset1:3
	ds_read2_b32 v[54:55], v138 offset0:8 offset1:9
	ds_read2_b32 v[56:57], v138 offset0:10 offset1:11
	ds_read2_b32 v[58:59], v138 offset0:16 offset1:17
	ds_read2_b32 v[60:61], v138 offset0:18 offset1:19
	ds_read2_b32 v[62:63], v138 offset0:24 offset1:25
	ds_read2_b32 v[64:65], v138 offset0:26 offset1:27
	ds_read_b128 v[142:145], v141
	ds_read_b128 v[146:149], v141 offset:32
	ds_read_b128 v[150:153], v141 offset:64
	ds_read_b128 v[154:157], v141 offset:96
	ds_read2_b32 v[34:35], v138 offset0:32 offset1:33
	ds_read2_b32 v[36:37], v138 offset0:34 offset1:35
	ds_read2_b32 v[38:39], v138 offset0:40 offset1:41
	ds_read2_b32 v[40:41], v138 offset0:42 offset1:43
	ds_read2_b32 v[42:43], v138 offset0:48 offset1:49
	ds_read2_b32 v[44:45], v138 offset0:50 offset1:51
	ds_read2_b32 v[46:47], v138 offset0:56 offset1:57
	ds_read2_b32 v[48:49], v138 offset0:58 offset1:59
	ds_read_b128 v[158:161], v141 offset:4608
	ds_read_b128 v[162:165], v141 offset:4640
	ds_read_b128 v[166:169], v141 offset:4672
	ds_read_b128 v[170:173], v141 offset:4704
	v_lshrrev_b32_e32 v174, v134, v102
	v_lshrrev_b32_e32 v175, v134, v103
	s_waitcnt lgkmcnt(15)
	v_bfe_i32 v176, v174, 0, 1
	v_bfe_i32 v177, v174, 1, 1
	v_bfe_i32 v178, v174, 2, 1
	v_bfe_i32 v179, v174, 3, 1
	v_bfi_b32 v50, v176, v50, v237
	v_bfi_b32 v51, v177, v51, v237
	v_bfi_b32 v52, v178, v52, v237
	v_bfi_b32 v53, v179, v53, v237
	v_bfe_i32 v176, v174, 8, 1
	v_bfe_i32 v177, v174, 9, 1
	v_bfe_i32 v178, v174, 10, 1
	v_bfe_i32 v179, v174, 11, 1
	v_bfi_b32 v54, v176, v54, v237
	v_bfi_b32 v55, v177, v55, v237
	v_bfi_b32 v56, v178, v56, v237
	v_bfi_b32 v57, v179, v57, v237
	v_bfe_i32 v176, v174, 16, 1
	v_bfe_i32 v177, v174, 17, 1
	v_bfe_i32 v178, v174, 18, 1
	v_bfe_i32 v179, v174, 19, 1
	v_bfi_b32 v58, v176, v58, v237
	v_bfi_b32 v59, v177, v59, v237
	v_bfi_b32 v60, v178, v60, v237
	v_bfi_b32 v61, v179, v61, v237
	v_bfe_i32 v176, v174, 24, 1
	v_bfe_i32 v177, v174, 25, 1
	v_bfe_i32 v178, v174, 26, 1
	v_bfe_i32 v179, v174, 27, 1
	v_bfi_b32 v62, v176, v62, v237
	v_bfi_b32 v63, v177, v63, v237
	v_bfi_b32 v64, v178, v64, v237
	v_bfi_b32 v65, v179, v65, v237
	s_waitcnt lgkmcnt(4)
	v_bfe_i32 v176, v175, 0, 1
	v_bfe_i32 v177, v175, 1, 1
	v_bfe_i32 v178, v175, 2, 1
	v_bfe_i32 v179, v175, 3, 1
	v_bfi_b32 v34, v176, v34, v237
	v_bfi_b32 v35, v177, v35, v237
	v_bfi_b32 v36, v178, v36, v237
	v_bfi_b32 v37, v179, v37, v237
	v_bfe_i32 v176, v175, 8, 1
	v_bfe_i32 v177, v175, 9, 1
	v_bfe_i32 v178, v175, 10, 1
	v_bfe_i32 v179, v175, 11, 1
	v_bfi_b32 v38, v176, v38, v237
	v_bfi_b32 v39, v177, v39, v237
	v_bfi_b32 v40, v178, v40, v237
	v_bfi_b32 v41, v179, v41, v237
	v_bfe_i32 v176, v175, 16, 1
	v_bfe_i32 v177, v175, 17, 1
	v_bfe_i32 v178, v175, 18, 1
	v_bfe_i32 v179, v175, 19, 1
	v_bfi_b32 v42, v176, v42, v237
	v_bfi_b32 v43, v177, v43, v237
	v_bfi_b32 v44, v178, v44, v237
	v_bfi_b32 v45, v179, v45, v237
	v_bfe_i32 v176, v175, 24, 1
	v_bfe_i32 v177, v175, 25, 1
	v_bfe_i32 v178, v175, 26, 1
	v_bfe_i32 v179, v175, 27, 1
	v_bfi_b32 v46, v176, v46, v237
	v_bfi_b32 v47, v177, v47, v237
	v_bfi_b32 v48, v178, v48, v237
	v_bfi_b32 v49, v179, v49, v237
	s_nop 1
	s_waitcnt lgkmcnt(3)
	v_mfma_f32_32x32x16_bf16 v[34:49], v[158:161], v[94:97], v[34:49]
	v_mfma_f32_32x32x16_bf16 v[50:65], v[142:145], v[94:97], v[50:65]
	s_waitcnt lgkmcnt(2)
	v_mfma_f32_32x32x16_bf16 v[34:49], v[162:165], v[90:93], v[34:49]
	v_mfma_f32_32x32x16_bf16 v[50:65], v[146:149], v[90:93], v[50:65]
	s_waitcnt lgkmcnt(1)
	v_mfma_f32_32x32x16_bf16 v[34:49], v[166:169], v[86:89], v[34:49]
	v_mfma_f32_32x32x16_bf16 v[50:65], v[150:153], v[86:89], v[50:65]
	s_waitcnt lgkmcnt(0)
	v_mfma_f32_32x32x16_bf16 v[34:49], v[170:173], v[82:85], v[34:49]
	v_mfma_f32_32x32x16_bf16 v[50:65], v[154:157], v[82:85], v[50:65]
	s_nop 11
; __device__ __forceinline__ unsigned cvtpk(float lo, float hi) { f32x2_t v = {lo, hi}; bf16x2_t b = __builtin_convertvector(v, bf16x2_t); return __builtin_bit_cast(unsigned, b); }
; __device__ __forceinline__ int crowc(int r) { return (r & 3) + 8 * (r >> 2); }
; template <int D, int DV, bool TAB, bool BITS, int KT> ...
;     ...
;         const int k0 = t * KT + sub * 64;
;         bool active = true;
;         if (TAB) active = (k0 <= qw_hi) && (k0 + 63 >= qw_lo - win);
;         if (active) {
;             const unsigned char* Kl = lds + KOFF + cur * KBUF + sub * 64 * KP; const unsigned char* Vl = lds + VOFF + cur * VBUF + sub * 128;
;             f32x16 p0, p1;
;             unsigned w0 = 0xffffffffu, w1 = 0xffffffffu;
;             if (BITS) { w0 = wq[2 * sub] >> (4 * hi); w1 = wq[2 * sub + 1] >> (4 * hi); }
;             const float nm = -mhat;
;             const int tj = TABN - 1 - TABOFF - qpos + k0 + 4 * hi;
;             constexpr int KG = (D > 64) ? 2 : 4;
;             if (D == 64) {
;                 bf16x8 ka[4], kb[4];
;                 if (TAB) {
; #pragma unroll
;                     for (int r = 0; r < 16; ++r) p0[r] = tabL[tj + crowc(r)]; }
; #pragma unroll
;                 for (int kk = 0; kk < 4; ++kk) ka[kk] = *(const bf16x8*)(Kl + r32 * KP + (kk * 16 + 8 * hi) * 2);
;                 if (TAB) {
; #pragma unroll
;                     for (int r = 0; r < 16; ++r) p1[r] = tabL[tj + 32 + crowc(r)]; }
; #pragma unroll
;                 for (int kk = 0; kk < 4; ++kk) kb[kk] = *(const bf16x8*)(Kl + (32 + r32) * KP + (kk * 16 + 8 * hi) * 2);
;     ...
; #pragma unroll
;             for (int g = 0; g < 4; ++g) {
;                 AT_VLOAD(vc, g);
;                 float e[8];
; #pragma unroll
;                 for (int i = 0; i < 8; ++i) { e[i] = __builtin_amdgcn_exp2f(g < 2 ? p0[(g & 1) * 8 + i] : p1[(g & 1) * 8 + i]); rs += e[i]; }
;                 u32x4v pw; pw.x = cvtpk(e[0], e[1]); pw.y = cvtpk(e[2], e[3]); pw.z = cvtpk(e[4], e[5]); pw.w = cvtpk(e[6], e[7]);
;                 const bf16x8 pa = __builtin_bit_cast(bf16x8, pw);
;                 __builtin_amdgcn_sched_barrier(0);
; #pragma unroll
;                 for (int dt = 0; dt < DV / 32; ++dt) o[dt] = __builtin_amdgcn_mfma_f32_32x32x16_bf16(pa, vc[dt], o[dt], 0, 0, 0);
;                 __builtin_amdgcn_sched_barrier(0x1 | 0x2 | 0x100);
;             }
.Ljoin_qk_c0:
.LBB0_957:
	v_exp_f32_e32 v50, v50
	v_exp_f32_e32 v51, v51
	v_exp_f32_e32 v52, v52
	v_exp_f32_e32 v53, v53
	v_add_u32_e32 v102, v140, v137
	v_add_f32_e32 v150, 0, v50
	v_exp_f32_e32 v54, v54
	v_add_u32_e32 v103, 0x9000, v102
	v_add_u32_e32 v102, 0xb000, v102
	v_add_f32_e32 v150, v51, v150
	v_exp_f32_e32 v55, v55
	ds_read2_b64 v[142:145], v103 offset1:2
	ds_read2_b64 v[146:149], v102 offset0:32 offset1:34
	v_add_f32_e32 v150, v52, v150
	v_exp_f32_e32 v56, v56
	v_exp_f32_e32 v57, v57
	v_add_f32_e32 v150, v53, v150
	v_add_f32_e32 v150, v54, v150
	v_add_f32_e32 v150, v55, v150
	v_add_f32_e32 v150, v56, v150
	v_cvt_pk_bf16_f32 v50, v50, v51
	v_cvt_pk_bf16_f32 v51, v52, v53
	v_cvt_pk_bf16_f32 v52, v54, v55
	v_cvt_pk_bf16_f32 v53, v56, v57
	v_exp_f32_e32 v58, v58
	v_exp_f32_e32 v59, v59
	s_waitcnt lgkmcnt(1)
	v_mfma_f32_32x32x16_bf16 v[18:33], v[50:53], v[142:145], v[18:33]
	v_exp_f32_e32 v60, v60
	v_add_f32_e32 v142, v57, v150
	v_exp_f32_e32 v61, v61
	v_add_f32_e32 v142, v58, v142
	v_exp_f32_e32 v62, v62
	v_add_f32_e32 v142, v59, v142
	v_exp_f32_e32 v63, v63
	s_waitcnt lgkmcnt(0)
	v_mfma_f32_32x32x16_bf16 v[2:17], v[50:53], v[146:149], v[2:17]
	ds_read2_b64 v[50:53], v103 offset0:4 offset1:6
	ds_read2_b64 v[54:57], v102 offset0:36 offset1:38
	v_add_f32_e32 v142, v60, v142
	v_exp_f32_e32 v64, v64
	v_exp_f32_e32 v65, v65
	v_add_f32_e32 v142, v61, v142
	v_add_f32_e32 v142, v62, v142
	v_add_f32_e32 v142, v63, v142
	v_add_f32_e32 v142, v64, v142
	v_cvt_pk_bf16_f32 v58, v58, v59
	v_cvt_pk_bf16_f32 v59, v60, v61
	v_cvt_pk_bf16_f32 v60, v62, v63
	v_cvt_pk_bf16_f32 v61, v64, v65
	v_exp_f32_e32 v34, v34
	v_exp_f32_e32 v35, v35
	s_waitcnt lgkmcnt(1)
	v_mfma_f32_32x32x16_bf16 v[18:33], v[58:61], v[50:53], v[18:33]
	v_exp_f32_e32 v36, v36
	v_exp_f32_e32 v37, v37
	v_exp_f32_e32 v38, v38
	v_exp_f32_e32 v39, v39
	v_exp_f32_e32 v40, v40
	v_exp_f32_e32 v41, v41
	s_waitcnt lgkmcnt(0)
	v_mfma_f32_32x32x16_bf16 v[2:17], v[58:61], v[54:57], v[2:17]
	v_add_f32_e32 v58, v65, v142
	v_add_f32_e32 v58, v34, v58
	ds_read2_b64 v[50:53], v103 offset0:8 offset1:10
	ds_read2_b64 v[54:57], v102 offset0:40 offset1:42
	v_add_f32_e32 v58, v35, v58
	v_add_f32_e32 v58, v36, v58
	v_add_f32_e32 v58, v37, v58
	v_add_f32_e32 v58, v38, v58
	v_add_f32_e32 v58, v39, v58
	v_add_f32_e32 v58, v40, v58
	v_cvt_pk_bf16_f32 v34, v34, v35
	v_cvt_pk_bf16_f32 v35, v36, v37
	v_cvt_pk_bf16_f32 v36, v38, v39
	v_cvt_pk_bf16_f32 v37, v40, v41
	v_exp_f32_e32 v42, v42
	v_exp_f32_e32 v43, v43
	s_waitcnt lgkmcnt(1)
	v_mfma_f32_32x32x16_bf16 v[18:33], v[34:37], v[50:53], v[18:33]
	v_exp_f32_e32 v44, v44
	v_add_f32_e32 v50, v41, v58
	v_exp_f32_e32 v45, v45
	v_add_f32_e32 v50, v42, v50
	v_exp_f32_e32 v46, v46
	v_add_f32_e32 v50, v43, v50
	v_exp_f32_e32 v47, v47
	s_waitcnt lgkmcnt(0)
	v_mfma_f32_32x32x16_bf16 v[2:17], v[34:37], v[54:57], v[2:17]
	ds_read2_b64 v[34:37], v103 offset0:12 offset1:14
	ds_read2_b64 v[38:41], v102 offset0:44 offset1:46
	v_add_f32_e32 v50, v44, v50
	v_exp_f32_e32 v48, v48
	v_exp_f32_e32 v49, v49
	v_add_f32_e32 v50, v45, v50
	v_add_f32_e32 v50, v46, v50
	v_add_f32_e32 v50, v47, v50
	v_add_f32_e32 v50, v48, v50
	v_cvt_pk_bf16_f32 v42, v42, v43
	v_cvt_pk_bf16_f32 v43, v44, v45
	v_cvt_pk_bf16_f32 v44, v46, v47
	v_cvt_pk_bf16_f32 v45, v48, v49
	s_waitcnt lgkmcnt(1)
	s_nop 0
	v_mfma_f32_32x32x16_bf16 v[18:33], v[42:45], v[34:37], v[18:33]
	v_add_f32_e32 v34, v49, v50
	v_add_f32_e32 v133, v133, v34
	v_cmp_lt_f32_e32 vcc, 0x43800000, v34
	s_waitcnt lgkmcnt(0)
	v_mfma_f32_32x32x16_bf16 v[2:17], v[42:45], v[38:41], v[2:17]
	s_cbranch_vccnz .Lrare_6
.Lback_6:
.LBB0_958:
	s_sub_i32 s9, s64, 64
	s_cmp_le_i32 s9, s73
	s_cselect_b64 s[12:13], -1, 0
	s_add_i32 s9, s64, -1
	s_cmp_ge_i32 s9, s74
	s_cselect_b64 s[52:53], -1, 0
	s_and_b64 s[12:13], s[12:13], s[52:53]
	s_andn2_b64 vcc, exec, s[12:13]
	s_cbranch_vccnz .LBB0_964
	s_cmp_lg_u32 s100, 0
	s_cbranch_scc1 .Lslow_qk_c1
	ds_read2_b32 v[50:51], v138 offset0:64 offset1:65
	ds_read2_b32 v[52:53], v138 offset0:66 offset1:67
	ds_read2_b32 v[54:55], v138 offset0:72 offset1:73
	ds_read2_b32 v[56:57], v138 offset0:74 offset1:75
	ds_read2_b32 v[58:59], v138 offset0:80 offset1:81
	ds_read2_b32 v[60:61], v138 offset0:82 offset1:83
	ds_read2_b32 v[62:63], v138 offset0:88 offset1:89
	ds_read2_b32 v[64:65], v138 offset0:90 offset1:91
	ds_read_b128 v[142:145], v141 offset:9216
	ds_read_b128 v[146:149], v141 offset:9248
	ds_read_b128 v[150:153], v141 offset:9280
	ds_read_b128 v[154:157], v141 offset:9312
	ds_read2_b32 v[34:35], v138 offset0:96 offset1:97
	ds_read2_b32 v[36:37], v138 offset0:98 offset1:99
	ds_read2_b32 v[38:39], v138 offset0:104 offset1:105
	ds_read2_b32 v[40:41], v138 offset0:106 offset1:107
	ds_read2_b32 v[42:43], v138 offset0:112 offset1:113
	ds_read2_b32 v[44:45], v138 offset0:114 offset1:115
	ds_read2_b32 v[46:47], v138 offset0:120 offset1:121
	ds_read2_b32 v[48:49], v138 offset0:122 offset1:123
	ds_read_b128 v[158:161], v141 offset:13824
	ds_read_b128 v[162:165], v141 offset:13856
	ds_read_b128 v[166:169], v141 offset:13888
	ds_read_b128 v[170:173], v141 offset:13920
	v_lshrrev_b32_e32 v174, v134, v104
	v_lshrrev_b32_e32 v175, v134, v105
	s_waitcnt lgkmcnt(15)
; __device__ __forceinline__ unsigned cvtpk(float lo, float hi) { f32x2_t v = {lo, hi}; bf16x2_t b = __builtin_convertvector(v, bf16x2_t); return __builtin_bit_cast(unsigned, b); }
; __device__ __forceinline__ int crowc(int r) { return (r & 3) + 8 * (r >> 2); }
; #define AT_VLOAD(dst, g) do { _Pragma("unroll") for (int dt = 0; dt < DV / 32; ++dt) { const unsigned char* vp = Vl + (dt * 32 + r32) * VP + (16 * (g) + 4 * hi) * 2; \
;                 const s16x4 lo = *(const s16x4*)vp, hh = *(const s16x4*)(vp + 16); dst[dt] = (bf16x8){lo[0], lo[1], lo[2], lo[3], hh[0], hh[1], hh[2], hh[3]}; } } while (0)
; template <int D, int DV, bool TAB, bool BITS, int KT> ...
;     ...
;                 for (int r = 0; r < 16; ++r) { if (TAB) p0[r] -= mhat; else p0[r] = nm; if (BITS) { if (!((w0 >> crowc(r)) & 1u)) p0[r] = NEGV; } }
;                 __builtin_amdgcn_sched_barrier(0);
; #pragma unroll
;                 for (int kk = 0; kk < 4; ++kk) p0 = __builtin_amdgcn_mfma_f32_32x32x16_bf16(ka[kk], qf[kk], p0, 0, 0, 0);
; #pragma unroll
;                 for (int r = 0; r < 16; ++r) { if (TAB) p1[r] -= mhat; else p1[r] = nm; if (BITS) { if (!((w1 >> crowc(r)) & 1u)) p1[r] = NEGV; } }
;                 __builtin_amdgcn_sched_barrier(0);
; #pragma unroll
;                 for (int kk = 0; kk < 4; ++kk) p1 = __builtin_amdgcn_mfma_f32_32x32x16_bf16(kb[kk], qf[kk], p1, 0, 0, 0);
;     ...
; #pragma unroll
;             for (int g = 0; g < 4; ++g) {
;                 AT_VLOAD(vc, g);
;                 float e[8];
; #pragma unroll
;                 for (int i = 0; i < 8; ++i) { e[i] = __builtin_amdgcn_exp2f(g < 2 ? p0[(g & 1) * 8 + i] : p1[(g & 1) * 8 + i]); rs += e[i]; }
;                 u32x4v pw; pw.x = cvtpk(e[0], e[1]); pw.y = cvtpk(e[2], e[3]); pw.z = cvtpk(e[4], e[5]); pw.w = cvtpk(e[6], e[7]);
;                 const bf16x8 pa = __builtin_bit_cast(bf16x8, pw);
;                 __builtin_amdgcn_sched_barrier(0);
; #pragma unroll
;                 for (int dt = 0; dt < DV / 32; ++dt) o[dt] = __builtin_amdgcn_mfma_f32_32x32x16_bf16(pa, vc[dt], o[dt], 0, 0, 0);
;                 __builtin_amdgcn_sched_barrier(0x1 | 0x2 | 0x100);
;             }
;             l_run += rs;
	v_bfe_i32 v176, v174, 0, 1
	v_bfe_i32 v177, v174, 1, 1
	v_bfe_i32 v178, v174, 2, 1
	v_bfe_i32 v179, v174, 3, 1
	v_bfi_b32 v50, v176, v50, v237
	v_bfi_b32 v51, v177, v51, v237
	v_bfi_b32 v52, v178, v52, v237
	v_bfi_b32 v53, v179, v53, v237
	v_bfe_i32 v176, v174, 8, 1
	v_bfe_i32 v177, v174, 9, 1
	v_bfe_i32 v178, v174, 10, 1
	v_bfe_i32 v179, v174, 11, 1
	v_bfi_b32 v54, v176, v54, v237
	v_bfi_b32 v55, v177, v55, v237
	v_bfi_b32 v56, v178, v56, v237
	v_bfi_b32 v57, v179, v57, v237
	v_bfe_i32 v176, v174, 16, 1
	v_bfe_i32 v177, v174, 17, 1
	v_bfe_i32 v178, v174, 18, 1
	v_bfe_i32 v179, v174, 19, 1
	v_bfi_b32 v58, v176, v58, v237
	v_bfi_b32 v59, v177, v59, v237
	v_bfi_b32 v60, v178, v60, v237
	v_bfi_b32 v61, v179, v61, v237
	v_bfe_i32 v176, v174, 24, 1
	v_bfe_i32 v177, v174, 25, 1
	v_bfe_i32 v178, v174, 26, 1
	v_bfe_i32 v179, v174, 27, 1
	v_bfi_b32 v62, v176, v62, v237
	v_bfi_b32 v63, v177, v63, v237
	v_bfi_b32 v64, v178, v64, v237
	v_bfi_b32 v65, v179, v65, v237
	s_waitcnt lgkmcnt(4)
	v_bfe_i32 v176, v175, 0, 1
	v_bfe_i32 v177, v175, 1, 1
	v_bfe_i32 v178, v175, 2, 1
	v_bfe_i32 v179, v175, 3, 1
	v_bfi_b32 v34, v176, v34, v237
	v_bfi_b32 v35, v177, v35, v237
	v_bfi_b32 v36, v178, v36, v237
	v_bfi_b32 v37, v179, v37, v237
	v_bfe_i32 v176, v175, 8, 1
	v_bfe_i32 v177, v175, 9, 1
	v_bfe_i32 v178, v175, 10, 1
	v_bfe_i32 v179, v175, 11, 1
	v_bfi_b32 v38, v176, v38, v237
	v_bfi_b32 v39, v177, v39, v237
	v_bfi_b32 v40, v178, v40, v237
	v_bfi_b32 v41, v179, v41, v237
	v_bfe_i32 v176, v175, 16, 1
	v_bfe_i32 v177, v175, 17, 1
	v_bfe_i32 v178, v175, 18, 1
	v_bfe_i32 v179, v175, 19, 1
	v_bfi_b32 v42, v176, v42, v237
	v_bfi_b32 v43, v177, v43, v237
	v_bfi_b32 v44, v178, v44, v237
	v_bfi_b32 v45, v179, v45, v237
	v_bfe_i32 v176, v175, 24, 1
	v_bfe_i32 v177, v175, 25, 1
	v_bfe_i32 v178, v175, 26, 1
	v_bfe_i32 v179, v175, 27, 1
	v_bfi_b32 v46, v176, v46, v237
	v_bfi_b32 v47, v177, v47, v237
	v_bfi_b32 v48, v178, v48, v237
	v_bfi_b32 v49, v179, v49, v237
	s_nop 1
	s_waitcnt lgkmcnt(3)
	v_mfma_f32_32x32x16_bf16 v[34:49], v[158:161], v[94:97], v[34:49]
	v_mfma_f32_32x32x16_bf16 v[50:65], v[142:145], v[94:97], v[50:65]
	s_waitcnt lgkmcnt(2)
	v_mfma_f32_32x32x16_bf16 v[34:49], v[162:165], v[90:93], v[34:49]
	v_mfma_f32_32x32x16_bf16 v[50:65], v[146:149], v[90:93], v[50:65]
	s_waitcnt lgkmcnt(1)
	v_mfma_f32_32x32x16_bf16 v[34:49], v[166:169], v[86:89], v[34:49]
	v_mfma_f32_32x32x16_bf16 v[50:65], v[150:153], v[86:89], v[50:65]
	s_waitcnt lgkmcnt(0)
	v_mfma_f32_32x32x16_bf16 v[34:49], v[170:173], v[82:85], v[34:49]
	v_mfma_f32_32x32x16_bf16 v[50:65], v[154:157], v[82:85], v[50:65]
	s_nop 11
.Ljoin_qk_c1:
.LBB0_963:
	v_exp_f32_e32 v50, v50
	v_exp_f32_e32 v51, v51
	v_exp_f32_e32 v52, v52
	v_exp_f32_e32 v53, v53
	v_add_u32_e32 v140, v140, v137
	v_add_f32_e32 v146, 0, v50
	v_exp_f32_e32 v54, v54
	v_add_u32_e32 v144, 0x9000, v140
	v_add_u32_e32 v145, 0xb000, v140
	v_add_f32_e32 v146, v51, v146
	v_exp_f32_e32 v55, v55
	ds_read2_b64 v[102:105], v144 offset0:16 offset1:18
	ds_read2_b64 v[140:143], v145 offset0:48 offset1:50
	v_add_f32_e32 v146, v52, v146
	v_exp_f32_e32 v56, v56
	v_exp_f32_e32 v57, v57
	v_add_f32_e32 v146, v53, v146
	v_add_f32_e32 v146, v54, v146
	v_add_f32_e32 v146, v55, v146
	v_add_f32_e32 v146, v56, v146
	v_cvt_pk_bf16_f32 v50, v50, v51
	v_cvt_pk_bf16_f32 v51, v52, v53
	v_cvt_pk_bf16_f32 v52, v54, v55
	v_cvt_pk_bf16_f32 v53, v56, v57
	v_exp_f32_e32 v58, v58
	v_exp_f32_e32 v59, v59
	s_waitcnt lgkmcnt(1)
	v_mfma_f32_32x32x16_bf16 v[18:33], v[50:53], v[102:105], v[18:33]
	v_exp_f32_e32 v60, v60
	v_add_f32_e32 v102, v57, v146
	v_exp_f32_e32 v61, v61
	v_add_f32_e32 v102, v58, v102
	v_exp_f32_e32 v62, v62
	v_add_f32_e32 v102, v59, v102
	v_exp_f32_e32 v63, v63
	s_waitcnt lgkmcnt(0)
	v_mfma_f32_32x32x16_bf16 v[2:17], v[50:53], v[140:143], v[2:17]
	ds_read2_b64 v[50:53], v144 offset0:20 offset1:22
	ds_read2_b64 v[54:57], v145 offset0:52 offset1:54
	v_add_f32_e32 v102, v60, v102
	v_exp_f32_e32 v64, v64
	v_exp_f32_e32 v65, v65
	v_add_f32_e32 v102, v61, v102
	v_add_f32_e32 v102, v62, v102
	v_add_f32_e32 v102, v63, v102
	v_add_f32_e32 v102, v64, v102
	v_cvt_pk_bf16_f32 v58, v58, v59
	v_cvt_pk_bf16_f32 v59, v60, v61
	v_cvt_pk_bf16_f32 v60, v62, v63
	v_cvt_pk_bf16_f32 v61, v64, v65
	v_exp_f32_e32 v34, v34
	v_exp_f32_e32 v35, v35
	s_waitcnt lgkmcnt(1)
	v_mfma_f32_32x32x16_bf16 v[18:33], v[58:61], v[50:53], v[18:33]
	v_exp_f32_e32 v36, v36
	v_exp_f32_e32 v37, v37
	v_exp_f32_e32 v38, v38
	v_exp_f32_e32 v39, v39
	v_exp_f32_e32 v40, v40
	v_exp_f32_e32 v41, v41
	s_waitcnt lgkmcnt(0)
	v_mfma_f32_32x32x16_bf16 v[2:17], v[58:61], v[54:57], v[2:17]
	v_add_f32_e32 v58, v65, v102
	v_add_f32_e32 v58, v34, v58
	ds_read2_b64 v[50:53], v144 offset0:24 offset1:26
	ds_read2_b64 v[54:57], v145 offset0:56 offset1:58
	v_add_f32_e32 v58, v35, v58
	v_add_f32_e32 v58, v36, v58
	v_add_f32_e32 v58, v37, v58
	v_add_f32_e32 v58, v38, v58
	v_add_f32_e32 v58, v39, v58
	v_add_f32_e32 v58, v40, v58
	v_cvt_pk_bf16_f32 v34, v34, v35
	v_cvt_pk_bf16_f32 v35, v36, v37
	v_cvt_pk_bf16_f32 v36, v38, v39
	v_cvt_pk_bf16_f32 v37, v40, v41
	v_exp_f32_e32 v42, v42
	v_exp_f32_e32 v43, v43
	s_waitcnt lgkmcnt(1)
	v_mfma_f32_32x32x16_bf16 v[18:33], v[34:37], v[50:53], v[18:33]
	v_exp_f32_e32 v44, v44
	v_add_f32_e32 v50, v41, v58
	v_exp_f32_e32 v45, v45
	v_add_f32_e32 v50, v42, v50
	v_exp_f32_e32 v46, v46
	v_add_f32_e32 v50, v43, v50
	v_exp_f32_e32 v47, v47
	s_waitcnt lgkmcnt(0)
	v_mfma_f32_32x32x16_bf16 v[2:17], v[34:37], v[54:57], v[2:17]
	ds_read2_b64 v[34:37], v144 offset0:28 offset1:30
	ds_read2_b64 v[38:41], v145 offset0:60 offset1:62
	v_add_f32_e32 v50, v44, v50
	v_exp_f32_e32 v48, v48
	v_exp_f32_e32 v49, v49
	v_add_f32_e32 v50, v45, v50
	v_add_f32_e32 v50, v46, v50
	v_add_f32_e32 v50, v47, v50
	v_add_f32_e32 v50, v48, v50
	v_cvt_pk_bf16_f32 v42, v42, v43
	v_cvt_pk_bf16_f32 v43, v44, v45
	v_cvt_pk_bf16_f32 v44, v46, v47
	v_cvt_pk_bf16_f32 v45, v48, v49
	s_waitcnt lgkmcnt(1)
	s_nop 0
	v_mfma_f32_32x32x16_bf16 v[18:33], v[42:45], v[34:37], v[18:33]
	v_add_f32_e32 v34, v49, v50
	v_add_f32_e32 v133, v133, v34
	v_cmp_lt_f32_e32 vcc, 0x43800000, v34
	s_waitcnt lgkmcnt(0)
	v_mfma_f32_32x32x16_bf16 v[2:17], v[42:45], v[38:41], v[2:17]
	s_cbranch_vccnz .Lrare_7
